# early L2 write-back: workgroups 504-511 (one per XCD, idle in the last partial round of ev_in / ffup / odin) issue buffer_wbl2 when they finish, so the barrier leader's release flush has less dirty da
# baseline (speedup 1.0000x reference)
.LBB0_448:
	s_cmp_lt_u32 s33, 0x1f8
	s_cbranch_scc1 .Learlyflush448
	s_waitcnt vmcnt(0)
	buffer_wbl2 sc1
	s_waitcnt vmcnt(0)
